# P8 K-loop: LDS-DMA loads use SGPR bases + 32-bit lane offsets (16 v_lshl_add_u64 per iteration removed, 4 SALU added)
# speedup vs baseline: 1.0044x; 1.0024x over previous
; #define PG8_STAGE(bufoff, gbase, voff) do { _Pragma("unroll") for (int _i = 0; _i < 2; ++_i) \
;         __builtin_amdgcn_global_load_lds((const unsigned*)((const char*)(gbase) + (voff)[_i]), (PG8_LAS unsigned*)(lds + (bufoff) + ldsw + _i * 8192), 16, 0, 0); } while (0)
; #define PG8_LDA(dst, b, h) do { _Pragma("unroll") for (int m = 0; m < 4; ++m) _Pragma("unroll") for (int k = 0; k < 2; ++k) dst[m][k] = *(const PG8_LAS bf16x8*)(lds + PG8_SA(b, h) + aoff + m * 2048 + k * 1024); } while (0)
; #define PG8_LDB(dst, b, h) do { _Pragma("unroll") for (int n = 0; n < 2; ++n) _Pragma("unroll") for (int k = 0; k < 2; ++k) dst[n][k] = *(const PG8_LAS bf16x8*)(lds + PG8_SB(b, h) + boff + n * 2048 + k * 1024); } while (0)
; #define PG8_MMA(ai, bj, At, Bt) do { __builtin_amdgcn_s_setprio(1); _Pragma("unroll") for (int m = 0; m < 4; ++m) _Pragma("unroll") for (int n = 0; n < 2; ++n) _Pragma("unroll") for (int k = 0; k < 2; ++k) \
;         acc[ai][bj][m][n] = __builtin_amdgcn_mfma_f32_16x16x32_bf16(Bt[n][k], At[m][k], acc[ai][bj][m][n], 0, 0, 0); __builtin_amdgcn_s_setprio(0); } while (0)
; #define PG8_WAIT_V(n) asm volatile("s_waitcnt vmcnt(" #n ")" ::: "memory")
; template <class Epi, class Sched, bool ALIGN_EPI = false, bool SP2 = false>
; __device__ __forceinline__ void gemm_phase(PG8_LAS unsigned char* lds, const Gemm g, const Sched& S, const Epi& E) {
;     ...
;             PG8_LDB(B0, 0, 0); PG8_LDB(B1, 0, 1); PG8_SCHED; PG8_LDA(At, 0, 0); PG8_STAGE(PG8_SA(1, 1), a1 + hstep, voffA);
;             PG8_WAIT_V(8); PG8_WAIT_L(0); PG8_BAR; PG8_MMA(0, 0, At, B0); PG8_MMA(0, 1, At, B1); PG8_BAR; PG8_SCHED;
;             PG8_LDA(At, 0, 1); PG8_STAGE(PG8_SB(0, 0), b2, voffB); PG8_STAGE(PG8_SB(0, 1), b2 + hstep, voffB); PG8_STAGE(PG8_SA(0, 0), a2, voffA);
;             PG8_WAIT_V(8); PG8_WAIT_L(0); PG8_BAR; PG8_MMA(1, 0, At, B0); PG8_MMA(1, 1, At, B1); PG8_BAR; PG8_SCHED;
;             PG8_LDB(B0, 1, 0); PG8_LDB(B1, 1, 1); PG8_SCHED; PG8_LDA(At, 1, 0); PG8_STAGE(PG8_SA(0, 1), a2 + hstep, voffA);
;             PG8_WAIT_V(8); PG8_WAIT_L(0); PG8_BAR; PG8_MMA(0, 0, At, B0); PG8_MMA(0, 1, At, B1); PG8_BAR; PG8_SCHED;
;             PG8_LDA(At, 1, 1); PG8_STAGE(PG8_SB(1, 0), b3, voffB); PG8_STAGE(PG8_SB(1, 1), b3 + hstep, voffB); PG8_STAGE(PG8_SA(1, 0), a3, voffA);
;             PG8_WAIT_V(8); PG8_WAIT_L(0); PG8_BAR; PG8_MMA(1, 0, At, B0); PG8_MMA(1, 1, At, B1); PG8_BAR; PG8_SCHED;
.LBB0_1175:
	ds_read_b128 v[152:155], v148
	ds_read_b128 v[156:159], v148 offset:1024
	ds_read_b128 v[160:163], v148 offset:2048
	ds_read_b128 v[164:167], v148 offset:3072
	ds_read_b128 v[168:171], v149
	ds_read_b128 v[172:175], v149 offset:1024
	ds_read_b128 v[176:179], v149 offset:2048
	ds_read_b128 v[180:183], v149 offset:3072
	s_add_u32 s3, s40, 0xfffc0080
	s_addc_u32 s42, s41, -1
	s_cmp_eq_u32 s55, 12
	s_cselect_b32 s45, s0, s42
	s_cselect_b32 s44, s1, s3
	s_cselect_b32 s43, s27, s54
	s_cselect_b32 s42, s29, s53
	s_add_i32 m0, s35, 0xc000
	ds_read_b128 v[184:187], v150
	ds_read_b128 v[188:191], v150 offset:1024
	ds_read_b128 v[192:195], v150 offset:2048
	ds_read_b128 v[196:199], v150 offset:3072
	ds_read_b128 v[200:203], v150 offset:4096
	ds_read_b128 v[204:207], v150 offset:5120
	ds_read_b128 v[208:211], v150 offset:6144
	ds_read_b128 v[212:215], v150 offset:7168
	global_load_lds_dwordx4 v138, s[40:41]
	s_add_i32 m0, s35, 0xe000
	s_nop 0
	global_load_lds_dwordx4 v140, s[40:41]
	s_waitcnt vmcnt(8)
	s_waitcnt lgkmcnt(0)
	s_barrier
	s_setprio 1
	s_waitcnt lgkmcnt(0)
	v_mfma_f32_16x16x32_bf16 v[126:129], v[152:155], v[184:187], v[126:129]
	v_mfma_f32_16x16x32_bf16 v[122:125], v[160:163], v[184:187], v[122:125]
	v_mfma_f32_16x16x32_bf16 v[110:113], v[152:155], v[192:195], v[110:113]
	v_mfma_f32_16x16x32_bf16 v[106:109], v[160:163], v[192:195], v[106:109]
	v_mfma_f32_16x16x32_bf16 v[94:97], v[152:155], v[200:203], v[94:97]
	v_mfma_f32_16x16x32_bf16 v[90:93], v[160:163], v[200:203], v[90:93]
	v_mfma_f32_16x16x32_bf16 v[78:81], v[152:155], v[208:211], v[78:81]
	v_mfma_f32_16x16x32_bf16 v[74:77], v[160:163], v[208:211], v[74:77]
	v_mfma_f32_16x16x32_bf16 v[126:129], v[156:159], v[188:191], v[126:129]
	v_mfma_f32_16x16x32_bf16 v[122:125], v[164:167], v[188:191], v[122:125]
	v_mfma_f32_16x16x32_bf16 v[110:113], v[156:159], v[196:199], v[110:113]
	v_mfma_f32_16x16x32_bf16 v[106:109], v[164:167], v[196:199], v[106:109]
	v_mfma_f32_16x16x32_bf16 v[94:97], v[156:159], v[204:207], v[94:97]
	v_mfma_f32_16x16x32_bf16 v[90:93], v[164:167], v[204:207], v[90:93]
	v_mfma_f32_16x16x32_bf16 v[78:81], v[156:159], v[212:215], v[78:81]
	v_mfma_f32_16x16x32_bf16 v[74:77], v[164:167], v[212:215], v[74:77]
	s_setprio 0
	s_setprio 1
	v_mfma_f32_16x16x32_bf16 v[118:121], v[168:171], v[184:187], v[118:121]
	v_mfma_f32_16x16x32_bf16 v[114:117], v[176:179], v[184:187], v[114:117]
	v_mfma_f32_16x16x32_bf16 v[102:105], v[168:171], v[192:195], v[102:105]
	v_mfma_f32_16x16x32_bf16 v[98:101], v[176:179], v[192:195], v[98:101]
	v_mfma_f32_16x16x32_bf16 v[86:89], v[168:171], v[200:203], v[86:89]
	v_mfma_f32_16x16x32_bf16 v[82:85], v[176:179], v[200:203], v[82:85]
	v_mfma_f32_16x16x32_bf16 v[70:73], v[168:171], v[208:211], v[70:73]
	v_mfma_f32_16x16x32_bf16 v[66:69], v[176:179], v[208:211], v[66:69]
	v_mfma_f32_16x16x32_bf16 v[118:121], v[172:175], v[188:191], v[118:121]
	v_mfma_f32_16x16x32_bf16 v[114:117], v[180:183], v[188:191], v[114:117]
	v_mfma_f32_16x16x32_bf16 v[102:105], v[172:175], v[196:199], v[102:105]
	v_mfma_f32_16x16x32_bf16 v[98:101], v[180:183], v[196:199], v[98:101]
	v_mfma_f32_16x16x32_bf16 v[86:89], v[172:175], v[204:207], v[86:89]
	v_mfma_f32_16x16x32_bf16 v[82:85], v[180:183], v[204:207], v[82:85]
	v_mfma_f32_16x16x32_bf16 v[70:73], v[172:175], v[212:215], v[70:73]
	v_mfma_f32_16x16x32_bf16 v[66:69], v[180:183], v[212:215], v[66:69]
	s_setprio 0
	s_barrier
	s_add_i32 s3, s33, s12
	s_mov_b32 m0, s3
	ds_read_b128 v[184:187], v150 offset:16384
	ds_read_b128 v[188:191], v150 offset:17408
	ds_read_b128 v[192:195], v150 offset:18432
	ds_read_b128 v[196:199], v150 offset:19456
	ds_read_b128 v[200:203], v150 offset:20480
	ds_read_b128 v[204:207], v150 offset:21504
	ds_read_b128 v[208:211], v150 offset:22528
	ds_read_b128 v[212:215], v150 offset:23552
	global_load_lds_dwordx4 v134, s[42:43]
	s_add_i32 m0, s3, 0x2000
	s_add_u32 s56, s42, 0x40000
	s_addc_u32 s57, s43, 0
	s_add_i32 s3, s50, s12
	global_load_lds_dwordx4 v130, s[42:43]
	s_mov_b32 m0, s3
	global_load_lds_dwordx4 v134, s[56:57]
	s_add_i32 m0, s3, 0x2000
	s_nop 0
	global_load_lds_dwordx4 v130, s[56:57]
	s_mov_b32 m0, s35
	s_nop 0
	global_load_lds_dwordx4 v136, s[44:45]
	s_mov_b32 m0, s39
	s_nop 0
	global_load_lds_dwordx4 v132, s[44:45]
	s_waitcnt vmcnt(8)
	s_waitcnt lgkmcnt(0)
	s_barrier
	s_setprio 1
	s_waitcnt lgkmcnt(0)
	v_mfma_f32_16x16x32_bf16 v[62:65], v[152:155], v[184:187], v[62:65]
	v_mfma_f32_16x16x32_bf16 v[58:61], v[160:163], v[184:187], v[58:61]
	v_mfma_f32_16x16x32_bf16 v[46:49], v[152:155], v[192:195], v[46:49]
	v_mfma_f32_16x16x32_bf16 v[42:45], v[160:163], v[192:195], v[42:45]
	v_mfma_f32_16x16x32_bf16 v[30:33], v[152:155], v[200:203], v[30:33]
	v_mfma_f32_16x16x32_bf16 v[26:29], v[160:163], v[200:203], v[26:29]
	v_mfma_f32_16x16x32_bf16 v[14:17], v[152:155], v[208:211], v[14:17]
	v_mfma_f32_16x16x32_bf16 v[10:13], v[160:163], v[208:211], v[10:13]
	v_mfma_f32_16x16x32_bf16 v[62:65], v[156:159], v[188:191], v[62:65]
	v_mfma_f32_16x16x32_bf16 v[58:61], v[164:167], v[188:191], v[58:61]
	v_mfma_f32_16x16x32_bf16 v[46:49], v[156:159], v[196:199], v[46:49]
	v_mfma_f32_16x16x32_bf16 v[42:45], v[164:167], v[196:199], v[42:45]
	v_mfma_f32_16x16x32_bf16 v[30:33], v[156:159], v[204:207], v[30:33]
	v_mfma_f32_16x16x32_bf16 v[26:29], v[164:167], v[204:207], v[26:29]
	v_mfma_f32_16x16x32_bf16 v[14:17], v[156:159], v[212:215], v[14:17]
	v_mfma_f32_16x16x32_bf16 v[10:13], v[164:167], v[212:215], v[10:13]
	s_setprio 0
	s_setprio 1
	v_mfma_f32_16x16x32_bf16 v[54:57], v[168:171], v[184:187], v[54:57]
	v_mfma_f32_16x16x32_bf16 v[50:53], v[176:179], v[184:187], v[50:53]
	v_mfma_f32_16x16x32_bf16 v[38:41], v[168:171], v[192:195], v[38:41]
	v_mfma_f32_16x16x32_bf16 v[34:37], v[176:179], v[192:195], v[34:37]
	v_mfma_f32_16x16x32_bf16 v[22:25], v[168:171], v[200:203], v[22:25]
	v_mfma_f32_16x16x32_bf16 v[18:21], v[176:179], v[200:203], v[18:21]
	v_mfma_f32_16x16x32_bf16 v[6:9], v[168:171], v[208:211], v[6:9]
	v_mfma_f32_16x16x32_bf16 v[2:5], v[176:179], v[208:211], v[2:5]
	v_mfma_f32_16x16x32_bf16 v[54:57], v[172:175], v[188:191], v[54:57]
	v_mfma_f32_16x16x32_bf16 v[50:53], v[180:183], v[188:191], v[50:53]
	v_mfma_f32_16x16x32_bf16 v[38:41], v[172:175], v[196:199], v[38:41]
	v_mfma_f32_16x16x32_bf16 v[34:37], v[180:183], v[196:199], v[34:37]
	v_mfma_f32_16x16x32_bf16 v[22:25], v[172:175], v[204:207], v[22:25]
	v_mfma_f32_16x16x32_bf16 v[18:21], v[180:183], v[204:207], v[18:21]
	v_mfma_f32_16x16x32_bf16 v[6:9], v[172:175], v[212:215], v[6:9]
	v_mfma_f32_16x16x32_bf16 v[2:5], v[180:183], v[212:215], v[2:5]
	s_setprio 0
	s_barrier
; #define PG8_STAGE(bufoff, gbase, voff) do { _Pragma("unroll") for (int _i = 0; _i < 2; ++_i) \
;         __builtin_amdgcn_global_load_lds((const unsigned*)((const char*)(gbase) + (voff)[_i]), (PG8_LAS unsigned*)(lds + (bufoff) + ldsw + _i * 8192), 16, 0, 0); } while (0)
; #define PG8_LDA(dst, b, h) do { _Pragma("unroll") for (int m = 0; m < 4; ++m) _Pragma("unroll") for (int k = 0; k < 2; ++k) dst[m][k] = *(const PG8_LAS bf16x8*)(lds + PG8_SA(b, h) + aoff + m * 2048 + k * 1024); } while (0)
; #define PG8_LDB(dst, b, h) do { _Pragma("unroll") for (int n = 0; n < 2; ++n) _Pragma("unroll") for (int k = 0; k < 2; ++k) dst[n][k] = *(const PG8_LAS bf16x8*)(lds + PG8_SB(b, h) + boff + n * 2048 + k * 1024); } while (0)
; #define PG8_MMA(ai, bj, At, Bt) do { __builtin_amdgcn_s_setprio(1); _Pragma("unroll") for (int m = 0; m < 4; ++m) _Pragma("unroll") for (int n = 0; n < 2; ++n) _Pragma("unroll") for (int k = 0; k < 2; ++k) \
;         acc[ai][bj][m][n] = __builtin_amdgcn_mfma_f32_16x16x32_bf16(Bt[n][k], At[m][k], acc[ai][bj][m][n], 0, 0, 0); __builtin_amdgcn_s_setprio(0); } while (0)
; #define PG8_WAIT_V(n) asm volatile("s_waitcnt vmcnt(" #n ")" ::: "memory")
; #define PG8_WAIT_L(n) asm volatile("s_waitcnt lgkmcnt(" #n ")" ::: "memory")
; #define PG8_BAR __builtin_amdgcn_s_barrier()
; #define PG8_SCHED __builtin_amdgcn_sched_barrier(0)
; template <class Epi, class Sched, bool ALIGN_EPI = false, bool SP2 = false>
; __device__ __forceinline__ void gemm_phase(PG8_LAS unsigned char* lds, const Gemm g, const Sched& S, const Epi& E) {
;     ...
;             PG8_LDB(B0, 1, 0); PG8_LDB(B1, 1, 1); PG8_SCHED; PG8_LDA(At, 1, 0); PG8_STAGE(PG8_SA(0, 1), a2 + hstep, voffA);
;             PG8_WAIT_V(8); PG8_WAIT_L(0); PG8_BAR; PG8_MMA(0, 0, At, B0); PG8_MMA(0, 1, At, B1); PG8_BAR; PG8_SCHED;
;             PG8_LDA(At, 1, 1); PG8_STAGE(PG8_SB(1, 0), b3, voffB); PG8_STAGE(PG8_SB(1, 1), b3 + hstep, voffB); PG8_STAGE(PG8_SA(1, 0), a3, voffA);
;             PG8_WAIT_V(8); PG8_WAIT_L(0); PG8_BAR; PG8_MMA(1, 0, At, B0); PG8_MMA(1, 1, At, B1); PG8_BAR; PG8_SCHED;
	s_add_i32 s3, 0, 0x18000
	v_add_u32_e32 v151, s3, v146
	s_add_i32 s56, 0, 0x1c000
	ds_read_b128 v[152:155], v151
	ds_read_b128 v[156:159], v151 offset:1024
	ds_read_b128 v[160:163], v151 offset:2048
	ds_read_b128 v[164:167], v151 offset:3072
	v_add_u32_e32 v151, s56, v146
	ds_read_b128 v[168:171], v151
	ds_read_b128 v[172:175], v151 offset:1024
	ds_read_b128 v[176:179], v151 offset:2048
	ds_read_b128 v[180:183], v151 offset:3072
	s_add_u32 s44, s44, 0x40000
	s_addc_u32 s45, s45, 0
	s_mov_b32 m0, s46
	ds_read_b128 v[184:187], v150 offset:32768
	ds_read_b128 v[188:191], v150 offset:33792
	ds_read_b128 v[192:195], v150 offset:34816
	ds_read_b128 v[196:199], v150 offset:35840
	ds_read_b128 v[200:203], v150 offset:36864
	ds_read_b128 v[204:207], v150 offset:37888
	ds_read_b128 v[208:211], v150 offset:38912
	ds_read_b128 v[212:215], v150 offset:39936
	global_load_lds_dwordx4 v136, s[44:45]
	s_mov_b32 m0, s47
	s_nop 0
	global_load_lds_dwordx4 v132, s[44:45]
	s_waitcnt vmcnt(8)
	s_waitcnt lgkmcnt(0)
	s_barrier
	s_setprio 1
	s_waitcnt lgkmcnt(0)
	v_mfma_f32_16x16x32_bf16 v[126:129], v[152:155], v[184:187], v[126:129]
	v_mfma_f32_16x16x32_bf16 v[122:125], v[160:163], v[184:187], v[122:125]
	v_mfma_f32_16x16x32_bf16 v[110:113], v[152:155], v[192:195], v[110:113]
	v_mfma_f32_16x16x32_bf16 v[106:109], v[160:163], v[192:195], v[106:109]
	v_mfma_f32_16x16x32_bf16 v[94:97], v[152:155], v[200:203], v[94:97]
	v_mfma_f32_16x16x32_bf16 v[90:93], v[160:163], v[200:203], v[90:93]
	v_mfma_f32_16x16x32_bf16 v[78:81], v[152:155], v[208:211], v[78:81]
	v_mfma_f32_16x16x32_bf16 v[74:77], v[160:163], v[208:211], v[74:77]
	v_mfma_f32_16x16x32_bf16 v[126:129], v[156:159], v[188:191], v[126:129]
	v_mfma_f32_16x16x32_bf16 v[122:125], v[164:167], v[188:191], v[122:125]
	v_mfma_f32_16x16x32_bf16 v[110:113], v[156:159], v[196:199], v[110:113]
	v_mfma_f32_16x16x32_bf16 v[106:109], v[164:167], v[196:199], v[106:109]
	v_mfma_f32_16x16x32_bf16 v[94:97], v[156:159], v[204:207], v[94:97]
	v_mfma_f32_16x16x32_bf16 v[90:93], v[164:167], v[204:207], v[90:93]
	v_mfma_f32_16x16x32_bf16 v[78:81], v[156:159], v[212:215], v[78:81]
	v_mfma_f32_16x16x32_bf16 v[74:77], v[164:167], v[212:215], v[74:77]
	s_setprio 0
	s_setprio 1
	v_mfma_f32_16x16x32_bf16 v[118:121], v[168:171], v[184:187], v[118:121]
	v_mfma_f32_16x16x32_bf16 v[114:117], v[176:179], v[184:187], v[114:117]
	v_mfma_f32_16x16x32_bf16 v[102:105], v[168:171], v[192:195], v[102:105]
	v_mfma_f32_16x16x32_bf16 v[98:101], v[176:179], v[192:195], v[98:101]
	v_mfma_f32_16x16x32_bf16 v[86:89], v[168:171], v[200:203], v[86:89]
	v_mfma_f32_16x16x32_bf16 v[82:85], v[176:179], v[200:203], v[82:85]
	v_mfma_f32_16x16x32_bf16 v[70:73], v[168:171], v[208:211], v[70:73]
	v_mfma_f32_16x16x32_bf16 v[66:69], v[176:179], v[208:211], v[66:69]
	v_mfma_f32_16x16x32_bf16 v[118:121], v[172:175], v[188:191], v[118:121]
	v_mfma_f32_16x16x32_bf16 v[114:117], v[180:183], v[188:191], v[114:117]
	v_mfma_f32_16x16x32_bf16 v[102:105], v[172:175], v[196:199], v[102:105]
	v_mfma_f32_16x16x32_bf16 v[98:101], v[180:183], v[196:199], v[98:101]
	v_mfma_f32_16x16x32_bf16 v[86:89], v[172:175], v[204:207], v[86:89]
	v_mfma_f32_16x16x32_bf16 v[82:85], v[180:183], v[204:207], v[82:85]
	v_mfma_f32_16x16x32_bf16 v[70:73], v[172:175], v[212:215], v[70:73]
	v_mfma_f32_16x16x32_bf16 v[66:69], v[180:183], v[212:215], v[66:69]
	s_setprio 0
	s_barrier
	s_add_i32 s3, s3, s12
	s_add_u32 s98, s42, 0x80
	s_addc_u32 s99, s43, 0
	s_add_u32 s100, s44, 0xfffc0080
	s_addc_u32 s101, s45, -1
	s_mov_b32 m0, s3
	ds_read_b128 v[184:187], v150 offset:49152
	ds_read_b128 v[188:191], v150 offset:50176
	ds_read_b128 v[192:195], v150 offset:51200
	ds_read_b128 v[196:199], v150 offset:52224
	ds_read_b128 v[200:203], v150 offset:53248
	ds_read_b128 v[204:207], v150 offset:54272
	ds_read_b128 v[208:211], v150 offset:55296
	ds_read_b128 v[212:215], v150 offset:56320
	global_load_lds_dwordx4 v134, s[98:99]
	s_add_i32 m0, s3, 0x2000
	s_add_u32 s42, s42, 0x40080
	s_addc_u32 s43, s43, 0
	s_add_i32 s3, s56, s12
	global_load_lds_dwordx4 v130, s[98:99]
	s_mov_b32 m0, s3
	s_nop 0
	global_load_lds_dwordx4 v134, s[42:43]
	s_add_i32 m0, s3, 0x2000
	s_nop 0
	global_load_lds_dwordx4 v130, s[42:43]
	s_mov_b32 m0, s48
	s_nop 0
	global_load_lds_dwordx4 v136, s[100:101]
	s_mov_b32 m0, s49
	s_nop 0
	global_load_lds_dwordx4 v132, s[100:101]
	s_waitcnt vmcnt(8)
	s_waitcnt lgkmcnt(0)
	s_barrier
	s_setprio 1
	s_waitcnt lgkmcnt(0)
	v_mfma_f32_16x16x32_bf16 v[62:65], v[152:155], v[184:187], v[62:65]
	s_add_i32 s55, s55, 2
	s_add_u32 s40, s40, 0x100
	s_addc_u32 s41, s41, 0
	s_add_u32 s53, s53, 0x100
	s_addc_u32 s54, s54, 0
	s_cmp_gt_u32 s55, 13
	v_mfma_f32_16x16x32_bf16 v[58:61], v[160:163], v[184:187], v[58:61]
	v_mfma_f32_16x16x32_bf16 v[46:49], v[152:155], v[192:195], v[46:49]
	v_mfma_f32_16x16x32_bf16 v[42:45], v[160:163], v[192:195], v[42:45]
	v_mfma_f32_16x16x32_bf16 v[30:33], v[152:155], v[200:203], v[30:33]
	v_mfma_f32_16x16x32_bf16 v[26:29], v[160:163], v[200:203], v[26:29]
	v_mfma_f32_16x16x32_bf16 v[14:17], v[152:155], v[208:211], v[14:17]
	v_mfma_f32_16x16x32_bf16 v[10:13], v[160:163], v[208:211], v[10:13]
	v_mfma_f32_16x16x32_bf16 v[62:65], v[156:159], v[188:191], v[62:65]
	v_mfma_f32_16x16x32_bf16 v[58:61], v[164:167], v[188:191], v[58:61]
	v_mfma_f32_16x16x32_bf16 v[46:49], v[156:159], v[196:199], v[46:49]
	v_mfma_f32_16x16x32_bf16 v[42:45], v[164:167], v[196:199], v[42:45]
	v_mfma_f32_16x16x32_bf16 v[30:33], v[156:159], v[204:207], v[30:33]
	v_mfma_f32_16x16x32_bf16 v[26:29], v[164:167], v[204:207], v[26:29]
	v_mfma_f32_16x16x32_bf16 v[14:17], v[156:159], v[212:215], v[14:17]
	v_mfma_f32_16x16x32_bf16 v[10:13], v[164:167], v[212:215], v[10:13]
	s_setprio 0
	s_setprio 1
	v_mfma_f32_16x16x32_bf16 v[54:57], v[168:171], v[184:187], v[54:57]
	v_mfma_f32_16x16x32_bf16 v[50:53], v[176:179], v[184:187], v[50:53]
	v_mfma_f32_16x16x32_bf16 v[38:41], v[168:171], v[192:195], v[38:41]
	v_mfma_f32_16x16x32_bf16 v[34:37], v[176:179], v[192:195], v[34:37]
	v_mfma_f32_16x16x32_bf16 v[22:25], v[168:171], v[200:203], v[22:25]
	v_mfma_f32_16x16x32_bf16 v[18:21], v[176:179], v[200:203], v[18:21]
	v_mfma_f32_16x16x32_bf16 v[6:9], v[168:171], v[208:211], v[6:9]
	v_mfma_f32_16x16x32_bf16 v[2:5], v[176:179], v[208:211], v[2:5]
	v_mfma_f32_16x16x32_bf16 v[54:57], v[172:175], v[188:191], v[54:57]
	v_mfma_f32_16x16x32_bf16 v[50:53], v[180:183], v[188:191], v[50:53]
	v_mfma_f32_16x16x32_bf16 v[38:41], v[172:175], v[196:199], v[38:41]
	v_mfma_f32_16x16x32_bf16 v[34:37], v[180:183], v[196:199], v[34:37]
	v_mfma_f32_16x16x32_bf16 v[22:25], v[172:175], v[204:207], v[22:25]
	v_mfma_f32_16x16x32_bf16 v[18:21], v[180:183], v[204:207], v[18:21]
	v_mfma_f32_16x16x32_bf16 v[6:9], v[172:175], v[212:215], v[6:9]
	v_mfma_f32_16x16x32_bf16 v[2:5], v[180:183], v[212:215], v[2:5]
	s_setprio 0
	s_barrier
	s_cbranch_scc0 .LBB0_1175
	s_and_b64 vcc, exec, s[16:17]
	s_cbranch_vccz .LBB0_1178
	s_barrier
